# system-scope streaming policy (sc0 sc1 nt) on the prompt-unit tail gate loads (read-once bf16 gate columns)
# speedup vs baseline: 1.0120x; 1.0120x over previous
; DI unsigned pk2(float a, float b) { f32x2 v = {a, b}; bf16x2v r = __builtin_convertvector(v, bf16x2v); return __builtin_bit_cast(unsigned, r); }
; DI float bflo(unsigned w) { return __uint_as_float(w << 16); }
; DI float bfhi(unsigned w) { return __uint_as_float(w & 0xffff0000u); }
; DI void store_gated(const AttnState& st, const bf16_t* sg, bf16_t* mo, int hh) {
; #pragma unroll
;     for (int dt = 0; dt < 2; ++dt)
; #pragma unroll
;         for (int g = 0; g < 4; ++g) {
;             const int d = 32 * dt + 8 * g + 4 * hh;
;             const u32x2 gv = *(const u32x2*)(sg + d);
;             const f32x16& o = dt == 0 ? st.o0 : st.o1;
;             const float a0 = o[4 * g] * bflo(gv[0]), a1 = o[4 * g + 1] * bfhi(gv[0]), a2 = o[4 * g + 2] * bflo(gv[1]), a3 = o[4 * g + 3] * bfhi(gv[1]);
;             *(u32x2*)(mo + d) = (u32x2){pk2(a0, a1), pk2(a2, a3)};
;         }
; }
; DI void prompt_sb_unit(const Params& p, int b, int h, int qt, char* smem) {
;     ...
;         if (qpos < LP) store_gated(st, p.u + (rowb + qpos) * NU + gcol, p.mix + (rowb + qpos) * DM + h * 64, hh);
.LBB0_432:
	s_or_b64 exec, exec, s[8:9]
	v_cmp_gt_i32_e32 vcc, s88, v98
	s_and_saveexec_b64 s[0:1], vcc
	s_xor_b64 s[0:1], exec, s[0:1]
	s_cbranch_execz .LBB0_418
	v_readfirstlane_b32 s36, v96
	s_mov_b32 s37, 0
	s_mov_b64 exec, -1
	s_lshl_b32 s10, s39, 1
	s_lshl_b64 s[8:9], s[36:37], 13
	s_add_u32 s8, s8, s68
	s_addc_u32 s9, s9, s69
	s_add_u32 s8, s8, s10
	s_addc_u32 s9, s9, 0
	s_add_u32 s8, s8, 0xc00
	s_addc_u32 s9, s9, 0
	s_lshl_b64 s[34:35], s[36:37], 11
	s_add_u32 s34, s34, s70
	s_addc_u32 s35, s35, s71
	s_add_u32 s34, s34, s10
	s_addc_u32 s35, s35, 0
	v_lshrrev_b32_e32 v38, 3, v174
	v_and_b32_e32 v36, 7, v174
	v_lshlrev_b32_e32 v36, 4, v36
	v_lshl_or_b32 v32, v38, 13, v36
	v_lshl_or_b32 v33, v38, 11, v36
	v_mul_u32_u24_e32 v38, 0x90, v38
	v_add_u32_e32 v36, v36, v38
	v_lshrrev_b32_e32 v38, 6, v138
	v_mul_u32_u24_e32 v38, 0x2400, v38
	v_add_u32_e32 v38, 0x100, v38
	v_add_u32_e32 v36, v36, v38
	v_and_b32_e32 v37, 31, v174
	v_mul_u32_u24_e32 v37, 0x90, v37
	v_add_u32_e32 v37, v37, v38
	v_lshrrev_b32_e32 v38, 5, v174
	v_lshl_add_u32 v37, v38, 3, v37
	global_load_dwordx4 v[40:43], v32, s[8:9] sc0 sc1 nt
	s_add_u32 s8, s8, 0x10000
	s_addc_u32 s9, s9, 0
	global_load_dwordx4 v[44:47], v32, s[8:9] sc0 sc1 nt
	s_add_u32 s8, s8, 0x10000
	s_addc_u32 s9, s9, 0
	global_load_dwordx4 v[48:51], v32, s[8:9] sc0 sc1 nt
	s_add_u32 s8, s8, 0x10000
	s_addc_u32 s9, s9, 0
	global_load_dwordx4 v[52:55], v32, s[8:9] sc0 sc1 nt
	s_waitcnt vmcnt(0) lgkmcnt(0)
	ds_write_b128 v36, v[40:43]
	ds_write_b128 v36, v[44:47] offset:1152
	ds_write_b128 v36, v[48:51] offset:2304
	ds_write_b128 v36, v[52:55] offset:3456
	s_waitcnt lgkmcnt(0)
	ds_read_b64 v[40:41], v37
	ds_read_b64 v[42:43], v37 offset:16
	ds_read_b64 v[44:45], v37 offset:32
	ds_read_b64 v[46:47], v37 offset:48
	ds_read_b64 v[48:49], v37 offset:64
	ds_read_b64 v[50:51], v37 offset:80
	ds_read_b64 v[52:53], v37 offset:96
	ds_read_b64 v[54:55], v37 offset:112
	s_waitcnt lgkmcnt(7)
	v_lshlrev_b32_e32 v56, 16, v40
	v_and_b32_e32 v57, 0xffff0000, v40
	v_lshlrev_b32_e32 v58, 16, v41
	v_and_b32_e32 v59, 0xffff0000, v41
	v_pk_mul_f32 v[16:17], v[16:17], v[56:57]
	v_pk_mul_f32 v[18:19], v[18:19], v[58:59]
	v_cvt_pk_bf16_f32 v16, v16, v17
	v_cvt_pk_bf16_f32 v17, v18, v19
	s_waitcnt lgkmcnt(6)
	v_lshlrev_b32_e32 v60, 16, v42
	v_and_b32_e32 v61, 0xffff0000, v42
	v_lshlrev_b32_e32 v62, 16, v43
	v_and_b32_e32 v63, 0xffff0000, v43
	v_pk_mul_f32 v[20:21], v[20:21], v[60:61]
	v_pk_mul_f32 v[22:23], v[22:23], v[62:63]
	v_cvt_pk_bf16_f32 v20, v20, v21
	v_cvt_pk_bf16_f32 v21, v22, v23
	s_waitcnt lgkmcnt(5)
	v_lshlrev_b32_e32 v56, 16, v44
	v_and_b32_e32 v57, 0xffff0000, v44
	v_lshlrev_b32_e32 v58, 16, v45
	v_and_b32_e32 v59, 0xffff0000, v45
	v_pk_mul_f32 v[24:25], v[24:25], v[56:57]
	v_pk_mul_f32 v[26:27], v[26:27], v[58:59]
	v_cvt_pk_bf16_f32 v24, v24, v25
	v_cvt_pk_bf16_f32 v25, v26, v27
	s_waitcnt lgkmcnt(4)
	v_lshlrev_b32_e32 v60, 16, v46
	v_and_b32_e32 v61, 0xffff0000, v46
	v_lshlrev_b32_e32 v62, 16, v47
	v_and_b32_e32 v63, 0xffff0000, v47
	v_pk_mul_f32 v[28:29], v[28:29], v[60:61]
	v_pk_mul_f32 v[30:31], v[30:31], v[62:63]
	v_cvt_pk_bf16_f32 v28, v28, v29
	v_cvt_pk_bf16_f32 v29, v30, v31
	s_waitcnt lgkmcnt(3)
	v_lshlrev_b32_e32 v56, 16, v48
	v_and_b32_e32 v57, 0xffff0000, v48
	v_lshlrev_b32_e32 v58, 16, v49
	v_and_b32_e32 v59, 0xffff0000, v49
	v_pk_mul_f32 v[0:1], v[0:1], v[56:57]
	v_pk_mul_f32 v[2:3], v[2:3], v[58:59]
	v_cvt_pk_bf16_f32 v0, v0, v1
	v_cvt_pk_bf16_f32 v1, v2, v3
	s_waitcnt lgkmcnt(2)
	v_lshlrev_b32_e32 v60, 16, v50
	v_and_b32_e32 v61, 0xffff0000, v50
	v_lshlrev_b32_e32 v62, 16, v51
	v_and_b32_e32 v63, 0xffff0000, v51
	v_pk_mul_f32 v[4:5], v[4:5], v[60:61]
	v_pk_mul_f32 v[6:7], v[6:7], v[62:63]
	v_cvt_pk_bf16_f32 v4, v4, v5
	v_cvt_pk_bf16_f32 v5, v6, v7
	s_waitcnt lgkmcnt(1)
	v_lshlrev_b32_e32 v56, 16, v52
	v_and_b32_e32 v57, 0xffff0000, v52
	v_lshlrev_b32_e32 v58, 16, v53
	v_and_b32_e32 v59, 0xffff0000, v53
	v_pk_mul_f32 v[8:9], v[8:9], v[56:57]
	v_pk_mul_f32 v[10:11], v[10:11], v[58:59]
	v_cvt_pk_bf16_f32 v8, v8, v9
	v_cvt_pk_bf16_f32 v9, v10, v11
	s_waitcnt lgkmcnt(0)
	v_lshlrev_b32_e32 v60, 16, v54
	v_and_b32_e32 v61, 0xffff0000, v54
	v_lshlrev_b32_e32 v62, 16, v55
	v_and_b32_e32 v63, 0xffff0000, v55
	v_pk_mul_f32 v[12:13], v[12:13], v[60:61]
	v_pk_mul_f32 v[14:15], v[14:15], v[62:63]
	v_cvt_pk_bf16_f32 v12, v12, v13
	v_cvt_pk_bf16_f32 v13, v14, v15
	ds_write_b64 v37, v[16:17]
	ds_write_b64 v37, v[20:21] offset:16
	ds_write_b64 v37, v[24:25] offset:32
	ds_write_b64 v37, v[28:29] offset:48
	ds_write_b64 v37, v[0:1] offset:64
	ds_write_b64 v37, v[4:5] offset:80
	ds_write_b64 v37, v[8:9] offset:96
	ds_write_b64 v37, v[12:13] offset:112
	s_waitcnt lgkmcnt(0)
	ds_read_b128 v[40:43], v36
	ds_read_b128 v[44:47], v36 offset:1152
	ds_read_b128 v[48:51], v36 offset:2304
	ds_read_b128 v[52:55], v36 offset:3456
	s_waitcnt lgkmcnt(3)
	global_store_dwordx4 v33, v[40:43], s[34:35]
	s_add_u32 s34, s34, 0x4000
	s_addc_u32 s35, s35, 0
	s_waitcnt lgkmcnt(2)
	global_store_dwordx4 v33, v[44:47], s[34:35]
	s_add_u32 s34, s34, 0x4000
	s_addc_u32 s35, s35, 0
	s_waitcnt lgkmcnt(1)
	global_store_dwordx4 v33, v[48:51], s[34:35]
	s_add_u32 s34, s34, 0x4000
	s_addc_u32 s35, s35, 0
	s_waitcnt lgkmcnt(0)
	global_store_dwordx4 v33, v[52:55], s[34:35]
	s_branch .LBB0_418

; DI unsigned pk2(float a, float b) { f32x2 v = {a, b}; bf16x2v r = __builtin_convertvector(v, bf16x2v); return __builtin_bit_cast(unsigned, r); }
; DI float bflo(unsigned w) { return __uint_as_float(w << 16); }
; DI float bfhi(unsigned w) { return __uint_as_float(w & 0xffff0000u); }
; DI void store_gated(const AttnState& st, const bf16_t* sg, bf16_t* mo, int hh) {
; #pragma unroll
;     for (int dt = 0; dt < 2; ++dt)
; #pragma unroll
;         for (int g = 0; g < 4; ++g) {
;             const int d = 32 * dt + 8 * g + 4 * hh;
;             const u32x2 gv = *(const u32x2*)(sg + d);
;             const f32x16& o = dt == 0 ? st.o0 : st.o1;
;             const float a0 = o[4 * g] * bflo(gv[0]), a1 = o[4 * g + 1] * bfhi(gv[0]), a2 = o[4 * g + 2] * bflo(gv[1]), a3 = o[4 * g + 3] * bfhi(gv[1]);
;             *(u32x2*)(mo + d) = (u32x2){pk2(a0, a1), pk2(a2, a3)};
;         }
; }
; template <int MODE>
; DI void prompt_unit(const Params& p, int b, int h, int qt, char* smem) {
;     ...
;     if (MODE == 1) { const float lt = st.l + __shfl_xor(st.l, 32); const float inv = 1.0f / lt; st.o0 = st.o0 * inv; st.o1 = st.o1 * inv; }
;     if (wave_valid && qpos < LP) store_gated(st, p.u + (rowb + qpos) * NU + gcol, p.mix + (rowb + qpos) * DM + (MODE == 0 ? 0 : 512) + h * 64, hh);
.LBB0_548:
	v_and_b32_e32 v33, 64, v174
	v_xor_b32_e32 v32, 32, v174
	v_add_u32_e32 v33, 64, v33
	v_cmp_lt_i32_e32 vcc, v32, v33
	s_nop 1
	v_cndmask_b32_e32 v32, v174, v32, vcc
	v_lshlrev_b32_e32 v32, 2, v32
	ds_bpermute_b32 v32, v32, v107
	v_cmp_gt_i32_e32 vcc, s88, v88
	s_and_b64 s[0:1], s[4:5], vcc
	s_and_saveexec_b64 s[4:5], s[0:1]
	s_xor_b64 s[0:1], exec, s[4:5]
	s_cbranch_execz .LBB0_507
	v_ashrrev_i32_e32 v89, 31, v88
	v_lshl_add_u64 v[34:35], v[88:89], 0, s[8:9]
	s_waitcnt lgkmcnt(0)
	v_add_f32_e32 v40, v107, v32
	v_div_scale_f32 v41, s[4:5], v40, v40, 1.0
	v_rcp_f32_e32 v43, v41
	v_div_scale_f32 v42, vcc, 1.0, v40, 1.0
	v_fma_f32 v44, -v41, v43, 1.0
	v_fmac_f32_e32 v43, v44, v43
	v_mul_f32_e32 v44, v42, v43
	v_fma_f32 v45, -v41, v44, v42
	v_fmac_f32_e32 v44, v45, v43
	v_fma_f32 v41, -v41, v44, v42
	v_div_fmas_f32 v41, v41, v43, v44
	v_div_fixup_f32 v40, v41, v40, 1.0
	v_readfirstlane_b32 s38, v34
	s_mov_b32 s39, 0
	s_mov_b64 exec, -1
	s_lshl_b64 s[46:47], s[38:39], 13
	s_add_u32 s46, s46, s68
	s_addc_u32 s47, s47, s69
	s_add_u32 s46, s46, s6
	s_addc_u32 s47, s47, 0
	s_add_u32 s46, s46, 0x1c00
	s_addc_u32 s47, s47, 0
	s_lshl_b64 s[48:49], s[38:39], 11
	s_add_u32 s48, s48, s70
	s_addc_u32 s49, s49, s71
	s_add_u32 s48, s48, s6
	s_addc_u32 s49, s49, 0
	s_add_u32 s48, s48, 0x400
	s_addc_u32 s49, s49, 0
	v_lshrrev_b32_e32 v33, 3, v174
	v_and_b32_e32 v38, 7, v174
	v_lshlrev_b32_e32 v38, 4, v38
	v_lshl_or_b32 v36, v33, 13, v38
	v_lshl_or_b32 v37, v33, 11, v38
	v_mul_u32_u24_e32 v33, 0x90, v33
	v_add_u32_e32 v38, v38, v33
	v_lshrrev_b32_e32 v33, 6, v138
	v_mul_u32_u24_e32 v33, 0x1200, v33
	v_add_u32_e32 v33, 0x10000, v33
	v_add_u32_e32 v38, v38, v33
	v_and_b32_e32 v39, 31, v174
	v_mul_u32_u24_e32 v39, 0x90, v39
	v_add_u32_e32 v39, v39, v33
	v_lshrrev_b32_e32 v33, 5, v174
	v_lshl_add_u32 v39, v33, 3, v39
	global_load_dwordx4 v[48:51], v36, s[46:47] sc0 sc1 nt
	s_add_u32 s46, s46, 0x10000
	s_addc_u32 s47, s47, 0
	global_load_dwordx4 v[52:55], v36, s[46:47] sc0 sc1 nt
	s_add_u32 s46, s46, 0x10000
	s_addc_u32 s47, s47, 0
	global_load_dwordx4 v[56:59], v36, s[46:47] sc0 sc1 nt
	s_add_u32 s46, s46, 0x10000
	s_addc_u32 s47, s47, 0
	global_load_dwordx4 v[60:63], v36, s[46:47] sc0 sc1 nt
	s_waitcnt vmcnt(0) lgkmcnt(0)
	ds_write_b128 v38, v[48:51]
	ds_write_b128 v38, v[52:55] offset:1152
	ds_write_b128 v38, v[56:59] offset:2304
	ds_write_b128 v38, v[60:63] offset:3456
	s_waitcnt lgkmcnt(0)
	ds_read_b64 v[48:49], v39
	ds_read_b64 v[50:51], v39 offset:16
	ds_read_b64 v[52:53], v39 offset:32
	ds_read_b64 v[54:55], v39 offset:48
	ds_read_b64 v[56:57], v39 offset:64
	ds_read_b64 v[58:59], v39 offset:80
	ds_read_b64 v[60:61], v39 offset:96
	ds_read_b64 v[62:63], v39 offset:112
	s_waitcnt lgkmcnt(7)
	v_lshlrev_b32_e32 v64, 16, v48
	v_and_b32_e32 v65, 0xffff0000, v48
	v_lshlrev_b32_e32 v66, 16, v49
	v_and_b32_e32 v67, 0xffff0000, v49
	v_pk_mul_f32 v[16:17], v[16:17], v[40:41] op_sel_hi:[1,0]
	v_pk_mul_f32 v[18:19], v[18:19], v[40:41] op_sel_hi:[1,0]
	v_pk_mul_f32 v[16:17], v[16:17], v[64:65]
	v_pk_mul_f32 v[18:19], v[18:19], v[66:67]
	v_cvt_pk_bf16_f32 v16, v16, v17
	v_cvt_pk_bf16_f32 v17, v18, v19
	s_waitcnt lgkmcnt(6)
	v_lshlrev_b32_e32 v68, 16, v50
	v_and_b32_e32 v69, 0xffff0000, v50
	v_lshlrev_b32_e32 v70, 16, v51
	v_and_b32_e32 v71, 0xffff0000, v51
	v_pk_mul_f32 v[20:21], v[20:21], v[40:41] op_sel_hi:[1,0]
	v_pk_mul_f32 v[22:23], v[22:23], v[40:41] op_sel_hi:[1,0]
	v_pk_mul_f32 v[20:21], v[20:21], v[68:69]
	v_pk_mul_f32 v[22:23], v[22:23], v[70:71]
	v_cvt_pk_bf16_f32 v20, v20, v21
	v_cvt_pk_bf16_f32 v21, v22, v23
	s_waitcnt lgkmcnt(5)
	v_lshlrev_b32_e32 v64, 16, v52
	v_and_b32_e32 v65, 0xffff0000, v52
	v_lshlrev_b32_e32 v66, 16, v53
	v_and_b32_e32 v67, 0xffff0000, v53
	v_pk_mul_f32 v[24:25], v[24:25], v[40:41] op_sel_hi:[1,0]
	v_pk_mul_f32 v[26:27], v[26:27], v[40:41] op_sel_hi:[1,0]
	v_pk_mul_f32 v[24:25], v[24:25], v[64:65]
	v_pk_mul_f32 v[26:27], v[26:27], v[66:67]
	v_cvt_pk_bf16_f32 v24, v24, v25
	v_cvt_pk_bf16_f32 v25, v26, v27
	s_waitcnt lgkmcnt(4)
	v_lshlrev_b32_e32 v68, 16, v54
	v_and_b32_e32 v69, 0xffff0000, v54
	v_lshlrev_b32_e32 v70, 16, v55
	v_and_b32_e32 v71, 0xffff0000, v55
	v_pk_mul_f32 v[28:29], v[28:29], v[40:41] op_sel_hi:[1,0]
	v_pk_mul_f32 v[30:31], v[30:31], v[40:41] op_sel_hi:[1,0]
	v_pk_mul_f32 v[28:29], v[28:29], v[68:69]
	v_pk_mul_f32 v[30:31], v[30:31], v[70:71]
	v_cvt_pk_bf16_f32 v28, v28, v29
	v_cvt_pk_bf16_f32 v29, v30, v31
	s_waitcnt lgkmcnt(3)
	v_lshlrev_b32_e32 v64, 16, v56
	v_and_b32_e32 v65, 0xffff0000, v56
	v_lshlrev_b32_e32 v66, 16, v57
	v_and_b32_e32 v67, 0xffff0000, v57
	v_pk_mul_f32 v[0:1], v[0:1], v[40:41] op_sel_hi:[1,0]
	v_pk_mul_f32 v[2:3], v[2:3], v[40:41] op_sel_hi:[1,0]
	v_pk_mul_f32 v[0:1], v[0:1], v[64:65]
	v_pk_mul_f32 v[2:3], v[2:3], v[66:67]
	v_cvt_pk_bf16_f32 v0, v0, v1
	v_cvt_pk_bf16_f32 v1, v2, v3
	s_waitcnt lgkmcnt(2)
	v_lshlrev_b32_e32 v68, 16, v58
	v_and_b32_e32 v69, 0xffff0000, v58
	v_lshlrev_b32_e32 v70, 16, v59
	v_and_b32_e32 v71, 0xffff0000, v59
	v_pk_mul_f32 v[4:5], v[4:5], v[40:41] op_sel_hi:[1,0]
	v_pk_mul_f32 v[6:7], v[6:7], v[40:41] op_sel_hi:[1,0]
	v_pk_mul_f32 v[4:5], v[4:5], v[68:69]
	v_pk_mul_f32 v[6:7], v[6:7], v[70:71]
	v_cvt_pk_bf16_f32 v4, v4, v5
	v_cvt_pk_bf16_f32 v5, v6, v7
	s_waitcnt lgkmcnt(1)
	v_lshlrev_b32_e32 v64, 16, v60
	v_and_b32_e32 v65, 0xffff0000, v60
	v_lshlrev_b32_e32 v66, 16, v61
	v_and_b32_e32 v67, 0xffff0000, v61
	v_pk_mul_f32 v[8:9], v[8:9], v[40:41] op_sel_hi:[1,0]
	v_pk_mul_f32 v[10:11], v[10:11], v[40:41] op_sel_hi:[1,0]
	v_pk_mul_f32 v[8:9], v[8:9], v[64:65]
	v_pk_mul_f32 v[10:11], v[10:11], v[66:67]
	v_cvt_pk_bf16_f32 v8, v8, v9
	v_cvt_pk_bf16_f32 v9, v10, v11
	s_waitcnt lgkmcnt(0)
	v_lshlrev_b32_e32 v68, 16, v62
	v_and_b32_e32 v69, 0xffff0000, v62
	v_lshlrev_b32_e32 v70, 16, v63
	v_and_b32_e32 v71, 0xffff0000, v63
	v_pk_mul_f32 v[12:13], v[12:13], v[40:41] op_sel_hi:[1,0]
	v_pk_mul_f32 v[14:15], v[14:15], v[40:41] op_sel_hi:[1,0]
	v_pk_mul_f32 v[12:13], v[12:13], v[68:69]
	v_pk_mul_f32 v[14:15], v[14:15], v[70:71]
	v_cvt_pk_bf16_f32 v12, v12, v13
	v_cvt_pk_bf16_f32 v13, v14, v15
	ds_write_b64 v39, v[16:17]
	ds_write_b64 v39, v[20:21] offset:16
	ds_write_b64 v39, v[24:25] offset:32
	ds_write_b64 v39, v[28:29] offset:48
	ds_write_b64 v39, v[0:1] offset:64
	ds_write_b64 v39, v[4:5] offset:80
	ds_write_b64 v39, v[8:9] offset:96
	ds_write_b64 v39, v[12:13] offset:112
	s_waitcnt lgkmcnt(0)
	ds_read_b128 v[48:51], v38
	ds_read_b128 v[52:55], v38 offset:1152
	ds_read_b128 v[56:59], v38 offset:2304
	ds_read_b128 v[60:63], v38 offset:3456
	s_waitcnt lgkmcnt(3)
	global_store_dwordx4 v37, v[48:51], s[48:49]
	s_add_u32 s48, s48, 0x4000
	s_addc_u32 s49, s49, 0
	s_waitcnt lgkmcnt(2)
	global_store_dwordx4 v37, v[52:55], s[48:49]
	s_add_u32 s48, s48, 0x4000
	s_addc_u32 s49, s49, 0
	s_waitcnt lgkmcnt(1)
	global_store_dwordx4 v37, v[56:59], s[48:49]
	s_add_u32 s48, s48, 0x4000
	s_addc_u32 s49, s49, 0
	s_waitcnt lgkmcnt(0)
	global_store_dwordx4 v37, v[60:63], s[48:49]
	s_branch .LBB0_507
